# P0 pool-weight fold: staging loads issued as one batch; P8 row-statistics exchange: redundant L1 invalidate removed
# speedup vs baseline: 1.0040x; 1.0040x over previous
; __global__ void __launch_bounds__(NTHR, 2) mk_fwd(Args args) {
;     ...
;           for (int wi = bid; wi < 256; wi += G) { const int g = wi >> 6, n0 = (wi & 63) * 16;
;               for (int e = tid; e < 128 * 128; e += NTHR) { const int k = e >> 7, c = e & 127; wmL[k * 129 + c] = wmix[g * 16384 + e] * pscale[g * 128 + c]; }
;               for (int e = tid; e < 128 * 16; e += NTHR) { const int c = e >> 4, j = e & 15; wpL[e] = wpool[(size_t)(g * 128 + c) * D + n0 + j]; }
;               __syncthreads();
.LBB0_20:
	s_ashr_i32 s0, s40, 6
	s_lshl_b32 s41, s0, 7
	s_lshl_b32 s4, s0, 14
	v_or_b32_e32 v6, s41, v15
	v_ashrrev_i32_e32 v7, 31, v6
	v_lshl_add_u64 v[6:7], v[6:7], 2, s[38:39]
	global_load_dword v6, v[6:7], off
	s_lshl_b32 s30, s4, 2
	s_add_u32 s98, s36, s30
	s_addc_u32 s99, s37, 0
	v_lshlrev_b32_e32 v25, 2, v188
	global_load_dword v100, v25, s[98:99]
	global_load_dword v101, v25, s[98:99] offset:2048
	s_add_u32 s98, s98, 0x1000
	s_addc_u32 s99, s99, 0
	global_load_dword v102, v25, s[98:99]
	global_load_dword v103, v25, s[98:99] offset:2048
	s_add_u32 s98, s98, 0x1000
	s_addc_u32 s99, s99, 0
	global_load_dword v104, v25, s[98:99]
	global_load_dword v105, v25, s[98:99] offset:2048
	s_add_u32 s98, s98, 0x1000
	s_addc_u32 s99, s99, 0
	global_load_dword v106, v25, s[98:99]
	global_load_dword v107, v25, s[98:99] offset:2048
	s_add_u32 s98, s98, 0x1000
	s_addc_u32 s99, s99, 0
	global_load_dword v108, v25, s[98:99]
	global_load_dword v109, v25, s[98:99] offset:2048
	s_add_u32 s98, s98, 0x1000
	s_addc_u32 s99, s99, 0
	global_load_dword v110, v25, s[98:99]
	global_load_dword v111, v25, s[98:99] offset:2048
	s_add_u32 s98, s98, 0x1000
	s_addc_u32 s99, s99, 0
	global_load_dword v112, v25, s[98:99]
	global_load_dword v113, v25, s[98:99] offset:2048
	s_add_u32 s98, s98, 0x1000
	s_addc_u32 s99, s99, 0
	global_load_dword v114, v25, s[98:99]
	global_load_dword v115, v25, s[98:99] offset:2048
	s_add_u32 s98, s98, 0x1000
	s_addc_u32 s99, s99, 0
	global_load_dword v116, v25, s[98:99]
	global_load_dword v117, v25, s[98:99] offset:2048
	s_add_u32 s98, s98, 0x1000
	s_addc_u32 s99, s99, 0
	global_load_dword v118, v25, s[98:99]
	global_load_dword v119, v25, s[98:99] offset:2048
	s_add_u32 s98, s98, 0x1000
	s_addc_u32 s99, s99, 0
	global_load_dword v120, v25, s[98:99]
	global_load_dword v121, v25, s[98:99] offset:2048
	s_add_u32 s98, s98, 0x1000
	s_addc_u32 s99, s99, 0
	global_load_dword v122, v25, s[98:99]
	global_load_dword v123, v25, s[98:99] offset:2048
	s_add_u32 s98, s98, 0x1000
	s_addc_u32 s99, s99, 0
	global_load_dword v124, v25, s[98:99]
	global_load_dword v125, v25, s[98:99] offset:2048
	s_add_u32 s98, s98, 0x1000
	s_addc_u32 s99, s99, 0
	global_load_dword v126, v25, s[98:99]
	global_load_dword v127, v25, s[98:99] offset:2048
	s_add_u32 s98, s98, 0x1000
	s_addc_u32 s99, s99, 0
	global_load_dword v128, v25, s[98:99]
	global_load_dword v129, v25, s[98:99] offset:2048
	s_add_u32 s98, s98, 0x1000
	s_addc_u32 s99, s99, 0
	global_load_dword v130, v25, s[98:99]
	global_load_dword v131, v25, s[98:99] offset:2048
	s_lshl_b32 s35, s40, 4
	s_and_b32 s34, s35, 0x3f0
	s_lshl_b32 s4, s34, 2
	v_lshl_add_u64 v[26:27], v[4:5], 0, s[4:5]
	v_add_u32_e32 v28, s41, v22
	v_lshlrev_b32_e32 v28, 12, v28
	v_mov_b32_e32 v29, 0
	s_mov_b64 s[100:101], 0x20000
	v_lshl_add_u64 v[26:27], v[26:27], 0, v[28:29]
	global_load_dword v132, v[26:27], off
	v_lshl_add_u64 v[26:27], v[26:27], 0, s[100:101]
	global_load_dword v133, v[26:27], off
	v_lshl_add_u64 v[26:27], v[26:27], 0, s[100:101]
	global_load_dword v134, v[26:27], off
	v_lshl_add_u64 v[26:27], v[26:27], 0, s[100:101]
	global_load_dword v135, v[26:27], off
	v_lshrrev_b32_e32 v30, 7, v188
	v_mad_u32_u24 v30, v30, s14, v0
	s_waitcnt vmcnt(0)
	v_mul_f32_e32 v100, v100, v6
	v_mul_f32_e32 v101, v101, v6
	v_mul_f32_e32 v102, v102, v6
	v_mul_f32_e32 v103, v103, v6
	v_mul_f32_e32 v104, v104, v6
	v_mul_f32_e32 v105, v105, v6
	v_mul_f32_e32 v106, v106, v6
	v_mul_f32_e32 v107, v107, v6
	v_mul_f32_e32 v108, v108, v6
	v_mul_f32_e32 v109, v109, v6
	v_mul_f32_e32 v110, v110, v6
	v_mul_f32_e32 v111, v111, v6
	v_mul_f32_e32 v112, v112, v6
	v_mul_f32_e32 v113, v113, v6
	v_mul_f32_e32 v114, v114, v6
	v_mul_f32_e32 v115, v115, v6
	v_mul_f32_e32 v116, v116, v6
	v_mul_f32_e32 v117, v117, v6
	v_mul_f32_e32 v118, v118, v6
	v_mul_f32_e32 v119, v119, v6
	v_mul_f32_e32 v120, v120, v6
	v_mul_f32_e32 v121, v121, v6
	v_mul_f32_e32 v122, v122, v6
	v_mul_f32_e32 v123, v123, v6
	v_mul_f32_e32 v124, v124, v6
	v_mul_f32_e32 v125, v125, v6
	v_mul_f32_e32 v126, v126, v6
	v_mul_f32_e32 v127, v127, v6
	v_mul_f32_e32 v128, v128, v6
	v_mul_f32_e32 v129, v129, v6
	v_mul_f32_e32 v130, v130, v6
	v_mul_f32_e32 v131, v131, v6
	ds_write_b32 v30, v100
	ds_write_b32 v30, v101 offset:2064
	ds_write_b32 v30, v102 offset:4128
	ds_write_b32 v30, v103 offset:6192
	ds_write_b32 v30, v104 offset:8256
	ds_write_b32 v30, v105 offset:10320
	ds_write_b32 v30, v106 offset:12384
	ds_write_b32 v30, v107 offset:14448
	ds_write_b32 v30, v108 offset:16512
	ds_write_b32 v30, v109 offset:18576
	ds_write_b32 v30, v110 offset:20640
	ds_write_b32 v30, v111 offset:22704
	ds_write_b32 v30, v112 offset:24768
	ds_write_b32 v30, v113 offset:26832
	ds_write_b32 v30, v114 offset:28896
	ds_write_b32 v30, v115 offset:30960
	ds_write_b32 v30, v116 offset:33024
	ds_write_b32 v30, v117 offset:35088
	ds_write_b32 v30, v118 offset:37152
	ds_write_b32 v30, v119 offset:39216
	ds_write_b32 v30, v120 offset:41280
	ds_write_b32 v30, v121 offset:43344
	ds_write_b32 v30, v122 offset:45408
	ds_write_b32 v30, v123 offset:47472
	ds_write_b32 v30, v124 offset:49536
	ds_write_b32 v30, v125 offset:51600
	ds_write_b32 v30, v126 offset:53664
	ds_write_b32 v30, v127 offset:55728
	ds_write_b32 v30, v128 offset:57792
	ds_write_b32 v30, v129 offset:59856
	ds_write_b32 v30, v130 offset:61920
	ds_write_b32 v30, v131 offset:63984
	ds_write_b32 v23, v132
	ds_write_b32 v23, v133 offset:2048
	ds_write_b32 v23, v134 offset:4096
	ds_write_b32 v23, v135 offset:6144
	v_mov_b32_e32 v8, 0
	s_movk_i32 s0, 0xe000
	v_mov_b32_e32 v2, v11
	v_mov_b32_e32 v9, v8
	v_mov_b32_e32 v6, v8
	v_mov_b32_e32 v7, v8
	s_waitcnt lgkmcnt(0)
	s_barrier

;     __device__ __forceinline__ void operator()(f32x4 (&acc)[2][2][4][2], const Unit& u, int wr, int wc, int fr, int fq) const {
;     ...
;         if (wid == 0) { bool dead = false; const unsigned long long t0 = __builtin_amdgcn_s_memrealtime();
;             for (;;) { if ((unsigned)__builtin_amdgcn_readfirstlane(__hip_atomic_load(cnt + 64 * u.pm, __ATOMIC_RELAXED, __HIP_MEMORY_SCOPE_AGENT)) >= 32u) break;
;                 if (__builtin_amdgcn_s_memrealtime() - t0 > 2000000ull) { dead = true; break; }
;                 __builtin_amdgcn_s_sleep(2); }
;             __builtin_amdgcn_fence(__ATOMIC_ACQUIRE, "agent");
;             if (lane == 0) flag[0] = dead ? 1u : 0u; }
.LBB0_1035:
	s_waitcnt lgkmcnt(0)
	s_and_b64 exec, exec, s[8:9]
	v_cndmask_b32_e64 v0, 0, 1, s[76:77]
	v_mov_b32_e32 v1, s90
	ds_write_b32 v1, v0

; #define LAS __attribute__((address_space(3)))
; __global__ void __launch_bounds__(NTHR, 2) mk_fwd(Args args) {
;     extern __shared__ __attribute__((aligned(16))) unsigned char lds_raw[];
;     LAS unsigned char* lds = (LAS unsigned char*)lds_raw;
	.amdhsa_kernel _Z6mk_fwd4Args
		.amdhsa_group_segment_fixed_size 0
		.amdhsa_private_segment_fixed_size 0
		.amdhsa_kernarg_size 408
		.amdhsa_user_sgpr_count 2
		.amdhsa_user_sgpr_dispatch_ptr 0
		.amdhsa_user_sgpr_queue_ptr 0
		.amdhsa_user_sgpr_kernarg_segment_ptr 1
		.amdhsa_user_sgpr_dispatch_id 0
		.amdhsa_user_sgpr_kernarg_preload_length 0
		.amdhsa_user_sgpr_kernarg_preload_offset 0
		.amdhsa_user_sgpr_private_segment_size 0
		.amdhsa_uses_dynamic_stack 0
		.amdhsa_enable_private_segment 0
		.amdhsa_system_sgpr_workgroup_id_x 1
		.amdhsa_system_sgpr_workgroup_id_y 0
		.amdhsa_system_sgpr_workgroup_id_z 0
		.amdhsa_system_sgpr_workgroup_info 0
		.amdhsa_system_vgpr_workitem_id 2
		.amdhsa_next_free_vgpr 247
		.amdhsa_next_free_sgpr 102
		.amdhsa_accum_offset 248
		.amdhsa_reserve_vcc 1
		.amdhsa_float_round_mode_32 0
		.amdhsa_float_round_mode_16_64 0
		.amdhsa_float_denorm_mode_32 3
		.amdhsa_float_denorm_mode_16_64 3
		.amdhsa_dx10_clamp 1
		.amdhsa_ieee_mode 1
		.amdhsa_fp16_overflow 0
		.amdhsa_tg_split 0
		.amdhsa_exception_fp_ieee_invalid_op 0
		.amdhsa_exception_fp_denorm_src 0
		.amdhsa_exception_fp_ieee_div_zero 0
		.amdhsa_exception_fp_ieee_overflow 0
		.amdhsa_exception_fp_ieee_underflow 0
		.amdhsa_exception_fp_ieee_inexact 0
		.amdhsa_exception_int_div_zero 0
	.end_amdhsa_kernel

; __global__ void __launch_bounds__(NTHR, 2) mk_fwd(Args args) {
amdhsa.kernels:
  - .agpr_count:     0
    .args:
      - .offset:         0
        .size:           152
        .value_kind:     by_value
      - .offset:         152
        .size:           4
        .value_kind:     hidden_block_count_x
      - .offset:         156
        .size:           4
        .value_kind:     hidden_block_count_y
      - .offset:         160
        .size:           4
        .value_kind:     hidden_block_count_z
      - .offset:         164
        .size:           2
        .value_kind:     hidden_group_size_x
      - .offset:         166
        .size:           2
        .value_kind:     hidden_group_size_y
      - .offset:         168
        .size:           2
        .value_kind:     hidden_group_size_z
      - .offset:         170
        .size:           2
        .value_kind:     hidden_remainder_x
      - .offset:         172
        .size:           2
        .value_kind:     hidden_remainder_y
      - .offset:         174
        .size:           2
        .value_kind:     hidden_remainder_z
      - .offset:         192
        .size:           8
        .value_kind:     hidden_global_offset_x
      - .offset:         200
        .size:           8
        .value_kind:     hidden_global_offset_y
      - .offset:         208
        .size:           8
        .value_kind:     hidden_global_offset_z
      - .offset:         216
        .size:           2
        .value_kind:     hidden_grid_dims
      - .offset:         240
        .size:           8
        .value_kind:     hidden_multigrid_sync_arg
      - .offset:         272
        .size:           4
        .value_kind:     hidden_dynamic_lds_size
    .group_segment_fixed_size: 0
    .kernarg_segment_align: 8
    .kernarg_segment_size: 408
    .language:       OpenCL C
    .language_version:
      - 2
      - 0
    .max_flat_workgroup_size: 512
    .name:           _Z6mk_fwd4Args
    .private_segment_fixed_size: 0
    .sgpr_count:     108
    .sgpr_spill_count: 12
    .symbol:         _Z6mk_fwd4Args.kd
    .uniform_work_group_size: 1
    .uses_dynamic_stack: false
    .vgpr_count:     247
    .vgpr_spill_count: 0
    .wavefront_size: 64
